# NSA epilogues: partial outputs kept in spare VGPRs between branches, gate vectors prefetched together
# speedup vs baseline: 1.0552x; 1.0054x over previous
; __device__ __forceinline__ unsigned cvt_pk_bf16(float lo, float hi) { unsigned r; asm("v_cvt_pk_bf16_f32 %0, %1, %2" : "=v"(r) : "v"(lo), "v"(hi)); return r; }
; __device__ __forceinline__ float bflo(unsigned w) { return __uint_as_float(w << 16); }
; __device__ __forceinline__ float bfhi(unsigned w) { return __uint_as_float(w & 0xffff0000u); }
; __device__ __forceinline__ float bf2f(bf16_t v) { return __uint_as_float(((unsigned)v) << 16); }
; __device__ __forceinline__ float sigmoidf_(float x) { return __builtin_amdgcn_rcpf(1.0f + __expf(-x)); }
; __device__ __forceinline__ void nsa_unit(LAS unsigned char* lds, const Ctx& P, int l, int b, int hkv, int tb) {
;     ...
; #pragma unroll
;         for (int sb = 0; sb < 2; ++sb) { const float g2 = sigmoidf_(bf2f(H[tok[sb] * LDH + C_GL + 32 + hq]) + P.in[21][l * 48 + 32 + hq]) / fmaxf(lsum[sb], 1e-30f);
; #pragma unroll
;             for (int dt = 0; dt < 4; ++dt) { const f32x4 r = park[(sb * 4 + dt) * 64] + o[sb][dt] * g2;
;                 const int d0 = 16 * dt + 4 * i; const u32x2 gg = *(const u32x2*)(H + tok[sb] * LDH + C_GC + hq * 64 + d0);
;                 u32x2 w; w.x = cvt_pk_bf16(r[0] * bflo(gg.x), r[1] * bfhi(gg.x)); w.y = cvt_pk_bf16(r[2] * bflo(gg.y), r[3] * bfhi(gg.y));
;                 *(u32x2*)(O + tok[sb] * DBR + hq * 64 + d0) = w; } }
.LBB0_183:
	v_mov_b64_e32 v[54:55], v[198:199]
	v_mov_b64_e32 v[56:57], v[200:201]
	v_mov_b32_e32 v2, s74
	ds_read_b64 v[58:59], v2
	v_max_f32_e32 v2, v161, v161
	v_max_f32_e32 v8, 0xda24260, v2
	v_max_f32_e32 v2, v159, v159
	v_max_f32_e32 v15, 0xda24260, v2
	v_readlane_b32 s94, v255, 39
	v_readlane_b32 s95, v255, 40
	v_readlane_b32 s44, v255, 47
.LBB0_184:
	s_mov_b64 s[0:1], 0x1400
	v_lshl_add_u64 v[6:7], v[124:125], 0, s[0:1]
	s_mov_b64 s[0:1], 0x1800
	v_mov_b32_e32 v133, v1
	v_lshl_add_u64 v[4:5], v[124:125], 0, s[0:1]
	s_mov_b64 s[0:1], 0x1c00
	v_lshl_add_u64 v[16:17], v[128:129], 0, v[132:133]
	v_lshl_add_u64 v[2:3], v[124:125], 0, s[0:1]
	v_readlane_b32 s0, v255, 56
	v_add_co_u32_e32 v16, vcc, 0x5000, v16
	v_readlane_b32 s1, v255, 57
	s_nop 0
	v_addc_co_u32_e32 v17, vcc, 0, v17, vcc
	v_lshl_add_u64 v[12:13], s[0:1], 0, v[0:1]
	global_load_ushort v9, v[16:17], off offset:1088
	v_lshlrev_b32_e32 v84, 1, v139
	v_mov_b32_e32 v85, v1
	v_lshl_add_u64 v[82:83], v[122:123], 0, v[132:133]
	v_add_co_u32_e32 v82, vcc, 0x5000, v82
	s_nop 1
	v_addc_co_u32_e32 v83, vcc, 0, v83, vcc
	global_load_ushort v80, v[82:83], off offset:1088
	v_lshl_add_u64 v[86:87], v[128:129], 0, v[0:1]
	v_lshl_add_u64 v[86:87], v[86:87], 0, v[84:85]
	v_add_co_u32_e32 v86, vcc, 0x3c00, v86
	s_nop 1
	v_addc_co_u32_e32 v87, vcc, 0, v87, vcc
	v_lshl_add_u64 v[88:89], v[122:123], 0, v[0:1]
	v_lshl_add_u64 v[88:89], v[88:89], 0, v[84:85]
	v_add_co_u32_e32 v88, vcc, 0x3c00, v88
	s_nop 1
	v_addc_co_u32_e32 v89, vcc, 0, v89, vcc
	global_load_dwordx2 v[60:61], v[86:87], off
	global_load_dwordx2 v[62:63], v[86:87], off offset:32
	global_load_dwordx2 v[64:65], v[86:87], off offset:64
	global_load_dwordx2 v[66:67], v[86:87], off offset:96
	global_load_dwordx2 v[68:69], v[88:89], off
	global_load_dwordx2 v[70:71], v[88:89], off offset:32
	global_load_dwordx2 v[72:73], v[88:89], off offset:64
	global_load_dwordx2 v[74:75], v[88:89], off offset:96
	s_waitcnt lgkmcnt(0)
	v_readfirstlane_b32 s1, v59
	v_readfirstlane_b32 s0, v58
	s_mov_b64 s[8:9], 0x3c00
	v_lshl_add_u64 v[10:11], v[124:125], 0, s[48:49]
	s_add_i32 s6, s6, s34
	s_cmpk_gt_i32 s6, 0x3ff
	s_mov_b32 s16, s7
	global_load_dword v14, v154, s[0:1] offset:128
	s_waitcnt vmcnt(1)
	v_lshlrev_b32_e32 v9, 16, v9
	s_waitcnt vmcnt(0)
; __device__ __forceinline__ unsigned cvt_pk_bf16(float lo, float hi) { unsigned r; asm("v_cvt_pk_bf16_f32 %0, %1, %2" : "=v"(r) : "v"(lo), "v"(hi)); return r; }
; __device__ __forceinline__ float bflo(unsigned w) { return __uint_as_float(w << 16); }
; __device__ __forceinline__ float bfhi(unsigned w) { return __uint_as_float(w & 0xffff0000u); }
; __device__ __forceinline__ float bf2f(bf16_t v) { return __uint_as_float(((unsigned)v) << 16); }
; __device__ __forceinline__ float sigmoidf_(float x) { return __builtin_amdgcn_rcpf(1.0f + __expf(-x)); }
; __device__ __forceinline__ void nsa_unit(LAS unsigned char* lds, const Ctx& P, int l, int b, int hkv, int tb) {
;     ...
; #pragma unroll
;         for (int sb = 0; sb < 2; ++sb) { const float g2 = sigmoidf_(bf2f(H[tok[sb] * LDH + C_GL + 32 + hq]) + P.in[21][l * 48 + 32 + hq]) / fmaxf(lsum[sb], 1e-30f);
; #pragma unroll
;             for (int dt = 0; dt < 4; ++dt) { const f32x4 r = park[(sb * 4 + dt) * 64] + o[sb][dt] * g2;
;                 const int d0 = 16 * dt + 4 * i; const u32x2 gg = *(const u32x2*)(H + tok[sb] * LDH + C_GC + hq * 64 + d0);
;                 u32x2 w; w.x = cvt_pk_bf16(r[0] * bflo(gg.x), r[1] * bfhi(gg.x)); w.y = cvt_pk_bf16(r[2] * bflo(gg.y), r[3] * bfhi(gg.y));
;                 *(u32x2*)(O + tok[sb] * DBR + hq * 64 + d0) = w; } }
	v_mov_b32_e32 v81, v14
	v_add_f32_e32 v9, v14, v9
	v_mul_f32_e32 v9, 0xbfb8aa3b, v9
	v_exp_f32_e32 v9, v9
	s_nop 0
	v_add_f32_e32 v9, 1.0, v9
	v_rcp_f32_e32 v9, v9
	s_nop 0
	v_div_scale_f32 v14, s[4:5], v8, v8, v9
	v_rcp_f32_e32 v16, v14
	s_movk_i32 s4, 0x3000
	v_fma_f32 v17, -v14, v16, 1.0
	v_fmac_f32_e32 v16, v17, v16
	v_div_scale_f32 v17, vcc, v9, v8, v9
	v_mul_f32_e32 v50, v17, v16
	v_fma_f32 v51, -v14, v50, v17
	v_fmac_f32_e32 v50, v51, v16
	v_fma_f32 v14, -v14, v50, v17
	v_div_fmas_f32 v14, v14, v16, v50
	v_div_fixup_f32 v14, v14, v8, v9
	v_lshlrev_b64 v[8:9], 11, v[126:127]
	v_lshl_add_u64 v[16:17], v[128:129], 0, v[0:1]
	v_lshl_add_u64 v[50:51], v[12:13], 0, v[8:9]
	v_lshlrev_b32_e32 v8, 1, v139
	v_mov_b32_e32 v9, v1
	v_lshl_add_u64 v[52:53], v[16:17], 0, v[8:9]
	v_lshl_add_u64 v[16:17], v[52:53], 0, s[8:9]
	v_add_co_u32_e32 v52, vcc, s4, v52
	v_pk_fma_f32 v[46:47], v[46:47], v[14:15], v[54:55] op_sel_hi:[1,0,1]
	s_nop 0
	v_addc_co_u32_e32 v53, vcc, 0, v53, vcc
	v_mov_b64_e32 v[52:53], v[60:61]
	v_pk_fma_f32 v[48:49], v[48:49], v[14:15], v[56:57] op_sel_hi:[1,0,1]
	v_lshlrev_b32_e32 v54, 16, v52
	v_and_b32_e32 v52, 0xffff0000, v52
	v_mul_f32_e32 v46, v46, v54
	v_mul_f32_e32 v47, v47, v52
	v_cvt_pk_bf16_f32 v52, v46, v47
	v_lshlrev_b32_e32 v46, 16, v53
	v_and_b32_e32 v47, 0xffff0000, v53
	v_mul_f32_e32 v46, v48, v46
	v_mul_f32_e32 v47, v49, v47
	v_cvt_pk_bf16_f32 v53, v46, v47
	v_lshl_add_u64 v[46:47], v[50:51], 0, v[8:9]
	global_store_dwordx2 v[46:47], v[52:53], off
	v_mov_b64_e32 v[48:49], v[202:203]
	v_mov_b64_e32 v[50:51], v[204:205]
	v_pk_fma_f32 v[42:43], v[42:43], v[14:15], v[48:49] op_sel_hi:[1,0,1]
	v_mov_b64_e32 v[48:49], v[62:63]
	v_pk_fma_f32 v[44:45], v[44:45], v[14:15], v[50:51] op_sel_hi:[1,0,1]
	v_lshlrev_b32_e32 v50, 16, v48
	v_and_b32_e32 v48, 0xffff0000, v48
	v_mul_f32_e32 v42, v42, v50
	v_mul_f32_e32 v43, v43, v48
	v_cvt_pk_bf16_f32 v42, v42, v43
	v_lshlrev_b32_e32 v43, 16, v49
	v_mul_f32_e32 v43, v44, v43
	v_and_b32_e32 v44, 0xffff0000, v49
	v_mul_f32_e32 v44, v45, v44
	v_cvt_pk_bf16_f32 v43, v43, v44
	global_store_dwordx2 v[46:47], v[42:43], off offset:32
	v_mov_b64_e32 v[42:43], v[206:207]
	v_mov_b64_e32 v[44:45], v[208:209]
	v_pk_fma_f32 v[38:39], v[38:39], v[14:15], v[42:43] op_sel_hi:[1,0,1]
	v_mov_b64_e32 v[42:43], v[64:65]
	v_pk_fma_f32 v[40:41], v[40:41], v[14:15], v[44:45] op_sel_hi:[1,0,1]
	v_lshlrev_b32_e32 v44, 16, v42
	v_and_b32_e32 v42, 0xffff0000, v42
	v_mul_f32_e32 v38, v38, v44
	v_mul_f32_e32 v39, v39, v42
	v_cvt_pk_bf16_f32 v38, v38, v39
	v_lshlrev_b32_e32 v39, 16, v43
	v_mul_f32_e32 v39, v40, v39
	v_and_b32_e32 v40, 0xffff0000, v43
	v_mul_f32_e32 v40, v41, v40
	v_cvt_pk_bf16_f32 v39, v39, v40
	global_store_dwordx2 v[46:47], v[38:39], off offset:64
	v_mov_b64_e32 v[38:39], v[210:211]
	v_mov_b64_e32 v[40:41], v[212:213]
	v_pk_fma_f32 v[36:37], v[36:37], v[14:15], v[40:41] op_sel_hi:[1,0,1]
	v_mov_b64_e32 v[16:17], v[66:67]
	v_pk_fma_f32 v[34:35], v[34:35], v[14:15], v[38:39] op_sel_hi:[1,0,1]
	v_lshlrev_b32_e32 v14, 16, v16
	v_and_b32_e32 v16, 0xffff0000, v16
	v_mul_f32_e32 v14, v34, v14
	v_mul_f32_e32 v16, v35, v16
	v_cvt_pk_bf16_f32 v16, v14, v16
	v_lshlrev_b32_e32 v14, 16, v17
	v_and_b32_e32 v17, 0xffff0000, v17
	v_mul_f32_e32 v17, v37, v17
	v_mul_f32_e32 v14, v36, v14
	v_cvt_pk_bf16_f32 v17, v14, v17
	global_store_dwordx2 v[46:47], v[16:17], off offset:96
	v_lshl_add_u64 v[16:17], v[122:123], 0, v[132:133]
	v_add_co_u32_e32 v16, vcc, s89, v16
	s_nop 1
	v_addc_co_u32_e32 v17, vcc, 0, v17, vcc
	v_mov_b32_e32 v14, v80
	v_lshlrev_b32_e32 v14, 16, v14
	v_mov_b32_e32 v16, v81
	v_add_f32_e32 v14, v16, v14
	v_mul_f32_e32 v14, 0xbfb8aa3b, v14
	v_exp_f32_e32 v14, v14
	s_nop 0
	v_add_f32_e32 v14, 1.0, v14
	v_rcp_f32_e32 v14, v14
	s_nop 0
	v_div_scale_f32 v16, s[0:1], v15, v15, v14
	v_rcp_f32_e32 v17, v16
	s_nop 0
	v_fma_f32 v34, -v16, v17, 1.0
	v_fmac_f32_e32 v17, v34, v17
	v_div_scale_f32 v34, vcc, v14, v15, v14
	v_mul_f32_e32 v35, v34, v17
	v_fma_f32 v36, -v16, v35, v34
	v_fmac_f32_e32 v35, v36, v17
	v_fma_f32 v16, -v16, v35, v34
	v_div_fmas_f32 v16, v16, v17, v35
	v_lshlrev_b64 v[34:35], 11, v[120:121]
	v_lshl_add_u64 v[34:35], v[12:13], 0, v[34:35]
	v_mov_b64_e32 v[10:11], v[214:215]
	v_mov_b64_e32 v[12:13], v[216:217]
	v_div_fixup_f32 v14, v16, v15, v14
	v_lshl_add_u64 v[16:17], v[122:123], 0, v[0:1]
	v_lshl_add_u64 v[16:17], v[16:17], 0, v[8:9]
	v_lshl_add_u64 v[8:9], v[34:35], 0, v[8:9]
	v_pk_fma_f32 v[30:31], v[30:31], v[14:15], v[10:11] op_sel_hi:[1,0,1]
	v_lshl_add_u64 v[10:11], v[16:17], 0, s[8:9]
	v_add_co_u32_e32 v16, vcc, s4, v16
	v_pk_fma_f32 v[12:13], v[32:33], v[14:15], v[12:13] op_sel_hi:[1,0,1]
	s_nop 0
	v_addc_co_u32_e32 v17, vcc, 0, v17, vcc
	v_mov_b64_e32 v[16:17], v[68:69]
	v_lshlrev_b32_e32 v0, 16, v16
	v_mul_f32_e32 v0, v30, v0
	v_and_b32_e32 v15, 0xffff0000, v16
	v_mul_f32_e32 v15, v31, v15
	v_cvt_pk_bf16_f32 v16, v0, v15
	v_lshlrev_b32_e32 v0, 16, v17
	v_mul_f32_e32 v0, v12, v0
	v_and_b32_e32 v12, 0xffff0000, v17
	v_mul_f32_e32 v12, v13, v12
	v_cvt_pk_bf16_f32 v17, v0, v12
	global_store_dwordx2 v[8:9], v[16:17], off
	v_mov_b64_e32 v[30:31], v[218:219]
	v_mov_b64_e32 v[32:33], v[220:221]
	v_pk_fma_f32 v[12:13], v[26:27], v[14:15], v[30:31] op_sel_hi:[1,0,1]
	v_mov_b64_e32 v[16:17], v[70:71]
	v_pk_fma_f32 v[6:7], v[28:29], v[14:15], v[32:33] op_sel_hi:[1,0,1]
	v_lshlrev_b32_e32 v0, 16, v16
	v_mul_f32_e32 v0, v12, v0
	v_and_b32_e32 v12, 0xffff0000, v16
	v_mul_f32_e32 v12, v13, v12
	v_cvt_pk_bf16_f32 v12, v0, v12
	v_lshlrev_b32_e32 v0, 16, v17
	v_mul_f32_e32 v0, v6, v0
	v_and_b32_e32 v6, 0xffff0000, v17
	v_mul_f32_e32 v6, v7, v6
	v_cvt_pk_bf16_f32 v13, v0, v6
	global_store_dwordx2 v[8:9], v[12:13], off offset:32
	v_mov_b64_e32 v[4:5], v[222:223]
	v_mov_b64_e32 v[6:7], v[224:225]
	v_pk_fma_f32 v[4:5], v[22:23], v[14:15], v[4:5] op_sel_hi:[1,0,1]
	v_mov_b64_e32 v[12:13], v[72:73]
	v_pk_fma_f32 v[6:7], v[24:25], v[14:15], v[6:7] op_sel_hi:[1,0,1]
	v_lshlrev_b32_e32 v0, 16, v12
	v_mul_f32_e32 v0, v4, v0
	v_and_b32_e32 v4, 0xffff0000, v12
	v_mul_f32_e32 v4, v5, v4
	v_and_b32_e32 v5, 0xffff0000, v13
	v_cvt_pk_bf16_f32 v4, v0, v4
	v_lshlrev_b32_e32 v0, 16, v13
	v_mul_f32_e32 v5, v7, v5
	v_mul_f32_e32 v0, v6, v0
	v_cvt_pk_bf16_f32 v5, v0, v5
	global_store_dwordx2 v[8:9], v[4:5], off offset:64
	v_mov_b64_e32 v[2:3], v[226:227]
	v_mov_b64_e32 v[4:5], v[228:229]
	v_pk_fma_f32 v[2:3], v[18:19], v[14:15], v[2:3] op_sel_hi:[1,0,1]
	v_mov_b64_e32 v[6:7], v[74:75]
	v_pk_fma_f32 v[4:5], v[20:21], v[14:15], v[4:5] op_sel_hi:[1,0,1]
	v_lshlrev_b32_e32 v0, 16, v6
	v_mul_f32_e32 v0, v2, v0
	v_and_b32_e32 v2, 0xffff0000, v6
	v_mul_f32_e32 v2, v3, v2
	v_and_b32_e32 v3, 0xffff0000, v7
	v_cvt_pk_bf16_f32 v2, v0, v2
	v_lshlrev_b32_e32 v0, 16, v7
	v_mul_f32_e32 v3, v5, v3
	v_mul_f32_e32 v0, v4, v0
	v_cvt_pk_bf16_f32 v3, v0, v3
	global_store_dwordx2 v[8:9], v[2:3], off offset:96
	s_cbranch_scc1 .LBB0_753

; __device__ __forceinline__ float bf2f(bf16_t v) { return __uint_as_float(((unsigned)v) << 16); }
; __device__ __forceinline__ float sigmoidf_(float x) { return __builtin_amdgcn_rcpf(1.0f + __expf(-x)); }
; __device__ __forceinline__ void nsa_unit(LAS unsigned char* lds, const Ctx& P, int l, int b, int hkv, int tb) {
;     ...
; #pragma unroll
;         for (int sb = 0; sb < 2; ++sb) { const float g1 = sigmoidf_(bf2f(H[tok[sb] * LDH + C_GL + 16 + hq]) + P.in[21][l * 48 + 16 + hq]) / fmaxf(lsum[sb], 1e-30f);
; #pragma unroll
;             for (int dt = 0; dt < 4; ++dt) park[(sb * 4 + dt) * 64] += o[sb][dt] * g1; }
;     }
;     {
;         f32x4 o[2][4]; float m[2], lsum[2];
; #pragma unroll
;         for (int sb = 0; sb < 2; ++sb) { m[sb] = NEGBIG; lsum[sb] = 0.f;
; #pragma unroll
;             for (int dt = 0; dt < 4; ++dt) o[sb][dt] = (f32x4){0.f, 0.f, 0.f, 0.f}; }
;         const bf16_t* kb = H + (size_t)b * SEQ * LDH + C_KW + hkv * 64; const bf16_t* vb = H + (size_t)b * SEQ * LDH + C_VW + hkv * 64;
;         const int kfirst = (t0 >= 256) ? 0 : (256 - t0) / 64;
.LBB0_597:
	global_load_dwordx4 v[198:201], v[124:125], off
	global_load_dwordx4 v[202:205], v[124:125], off offset:1024
	global_load_dwordx4 v[206:209], v[124:125], off offset:2048
	global_load_dwordx4 v[210:213], v[124:125], off offset:3072
	v_add_co_u32_e32 v230, vcc, 0x1000, v124
	s_nop 1
	v_addc_co_u32_e32 v231, vcc, 0, v125, vcc
	global_load_dwordx4 v[214:217], v[230:231], off
	global_load_dwordx4 v[218:221], v[230:231], off offset:1024
	global_load_dwordx4 v[222:225], v[230:231], off offset:2048
	global_load_dwordx4 v[226:229], v[230:231], off offset:3072
	v_mov_b32_e32 v133, v1
	v_lshl_add_u64 v[20:21], v[128:129], 0, v[132:133]
	v_add_co_u32_e32 v20, vcc, 0x5000, v20
	s_nop 1
	v_addc_co_u32_e32 v21, vcc, 0, v21, vcc
	global_load_ushort v20, v[20:21], off offset:1056
	v_mov_b32_e32 v21, s74
	ds_read_b64 v[58:59], v21
	v_add_u32_e32 v21, s71, v96
	v_lshlrev_b32_e32 v154, 2, v21
	s_waitcnt lgkmcnt(0)
	v_readfirstlane_b32 s1, v59
	v_readfirstlane_b32 s0, v58
	s_waitcnt vmcnt(0)
	v_lshlrev_b32_e32 v20, 16, v20
	s_nop 2
	global_load_dword v21, v154, s[0:1] offset:64
	s_waitcnt vmcnt(0)
	v_add_f32_e32 v20, v21, v20
	v_mul_f32_e32 v20, 0xbfb8aa3b, v20
	v_exp_f32_e32 v20, v20
	s_nop 0
	v_add_f32_e32 v20, 1.0, v20
	v_rcp_f32_e32 v20, v20
	s_nop 0
	v_div_scale_f32 v21, s[4:5], v19, v19, v20
	v_rcp_f32_e32 v54, v21
	s_nop 0
	v_fma_f32 v55, -v21, v54, 1.0
	v_fmac_f32_e32 v54, v55, v54
	v_div_scale_f32 v55, vcc, v20, v19, v20
	v_mul_f32_e32 v56, v55, v54
	v_fma_f32 v57, -v21, v56, v55
	v_fmac_f32_e32 v56, v57, v54
	v_fma_f32 v21, -v21, v56, v55
	v_div_fmas_f32 v21, v21, v54, v56
	v_mov_b64_e32 v[54:55], v[198:199]
	v_mov_b64_e32 v[56:57], v[200:201]
	v_div_fixup_f32 v20, v21, v19, v20
	v_pk_fma_f32 v[56:57], v[40:41], v[20:21], v[56:57] op_sel_hi:[1,0,1]
	v_pk_fma_f32 v[54:55], v[38:39], v[20:21], v[54:55] op_sel_hi:[1,0,1]
	v_mov_b64_e32 v[38:39], v[202:203]
	v_mov_b64_e32 v[40:41], v[204:205]
	v_pk_fma_f32 v[40:41], v[44:45], v[20:21], v[40:41] op_sel_hi:[1,0,1]
	v_pk_fma_f32 v[38:39], v[42:43], v[20:21], v[38:39] op_sel_hi:[1,0,1]
	v_mov_b64_e32 v[202:203], v[38:39]
	v_mov_b64_e32 v[204:205], v[40:41]
	v_mov_b64_e32 v[38:39], v[206:207]
	v_mov_b64_e32 v[40:41], v[208:209]
	s_nop 0
	v_mov_b64_e32 v[198:199], v[54:55]
	v_mov_b64_e32 v[200:201], v[56:57]
	v_pk_fma_f32 v[40:41], v[48:49], v[20:21], v[40:41] op_sel_hi:[1,0,1]
	v_pk_fma_f32 v[38:39], v[46:47], v[20:21], v[38:39] op_sel_hi:[1,0,1]
	v_mov_b64_e32 v[206:207], v[38:39]
	v_mov_b64_e32 v[208:209], v[40:41]
	v_mov_b64_e32 v[38:39], v[210:211]
	v_mov_b64_e32 v[40:41], v[212:213]
	v_pk_fma_f32 v[40:41], v[52:53], v[20:21], v[40:41] op_sel_hi:[1,0,1]
	v_pk_fma_f32 v[38:39], v[50:51], v[20:21], v[38:39] op_sel_hi:[1,0,1]
	v_lshl_add_u64 v[20:21], v[122:123], 0, v[132:133]
	v_add_co_u32_e32 v20, vcc, s89, v20
	v_mov_b64_e32 v[210:211], v[38:39]
	v_mov_b64_e32 v[212:213], v[40:41]
	s_nop 0
	v_addc_co_u32_e32 v21, vcc, 0, v21, vcc
	global_load_ushort v19, v[20:21], off offset:1056
	s_waitcnt vmcnt(0)
	v_lshlrev_b32_e32 v19, 16, v19
	global_load_dword v20, v154, s[0:1] offset:64
	s_waitcnt vmcnt(0)
	v_add_f32_e32 v19, v20, v19
	v_mul_f32_e32 v19, 0xbfb8aa3b, v19
	v_exp_f32_e32 v19, v19
	s_nop 0
	v_add_f32_e32 v19, 1.0, v19
	v_rcp_f32_e32 v19, v19
	s_nop 0
	v_div_scale_f32 v20, s[0:1], v18, v18, v19
	v_rcp_f32_e32 v21, v20
	s_sub_i32 s0, 0x100, s55
	s_lshr_b32 s0, s0, 6
	s_cmp_lt_i32 s54, 4
	v_fma_f32 v38, -v20, v21, 1.0
	v_fmac_f32_e32 v21, v38, v21
	v_div_scale_f32 v38, vcc, v19, v18, v19
	v_mul_f32_e32 v39, v38, v21
	v_fma_f32 v40, -v20, v39, v38
	v_fmac_f32_e32 v39, v40, v21
	v_fma_f32 v20, -v20, v39, v38
	v_div_fmas_f32 v20, v20, v21, v39
	v_add_co_u32_e32 v40, vcc, s88, v124
	v_div_fixup_f32 v38, v20, v18, v19
	s_nop 0
	v_addc_co_u32_e32 v41, vcc, 0, v125, vcc
	v_mov_b64_e32 v[18:19], v[214:215]
	v_mov_b64_e32 v[20:21], v[216:217]
	s_cselect_b32 s0, s0, 0
	s_cmp_lt_u32 s0, 5
	v_pk_fma_f32 v[20:21], v[24:25], v[38:39], v[20:21] op_sel_hi:[1,0,1]
	v_pk_fma_f32 v[18:19], v[22:23], v[38:39], v[18:19] op_sel_hi:[1,0,1]
	v_mov_b64_e32 v[214:215], v[18:19]
	v_mov_b64_e32 v[216:217], v[20:21]
	v_mov_b64_e32 v[18:19], v[218:219]
	v_mov_b64_e32 v[20:21], v[220:221]
	v_pk_fma_f32 v[18:19], v[26:27], v[38:39], v[18:19] op_sel_hi:[1,0,1]
	v_pk_fma_f32 v[20:21], v[28:29], v[38:39], v[20:21] op_sel_hi:[1,0,1]
	v_mov_b64_e32 v[218:219], v[18:19]
	v_mov_b64_e32 v[220:221], v[20:21]
	v_mov_b64_e32 v[18:19], v[222:223]
	v_mov_b64_e32 v[20:21], v[224:225]
	v_pk_fma_f32 v[18:19], v[34:35], v[38:39], v[18:19] op_sel_hi:[1,0,1]
	v_pk_fma_f32 v[20:21], v[36:37], v[38:39], v[20:21] op_sel_hi:[1,0,1]
	v_mov_b64_e32 v[222:223], v[18:19]
	v_mov_b64_e32 v[224:225], v[20:21]
	v_mov_b64_e32 v[18:19], v[226:227]
	v_mov_b64_e32 v[20:21], v[228:229]
	v_pk_fma_f32 v[18:19], v[30:31], v[38:39], v[18:19] op_sel_hi:[1,0,1]
	v_pk_fma_f32 v[20:21], v[32:33], v[38:39], v[20:21] op_sel_hi:[1,0,1]
	v_mov_b64_e32 v[226:227], v[18:19]
	v_mov_b64_e32 v[228:229], v[20:21]
	s_cbranch_scc0 .LBB0_752
	s_lshl_b32 s1, s18, 1
	s_add_u32 s4, s16, s1
	s_addc_u32 s5, s17, 0
	v_mov_b32_e32 v87, v1
	v_lshl_add_u64 v[18:19], s[4:5], 0, v[86:87]
	s_mov_b64 s[8:9], 0x3800
	v_lshl_add_u64 v[134:135], v[18:19], 0, s[8:9]
	v_lshl_add_u64 v[18:19], v[94:95], 1, s[4:5]
	s_mov_b64 s[4:5], 0x3a00
	v_lshl_add_u64 v[136:137], v[18:19], 0, s[4:5]
	v_lshlrev_b32_e32 v18, 4, v103
	v_sub_u32_e32 v18, v153, v18
	v_add_u32_e32 v133, 0, v18
	v_lshlrev_b32_e32 v18, 2, v144
	v_lshlrev_b32_e32 v19, 2, v97
	s_movk_i32 s1, 0xff80
	v_and_or_b32 v18, v18, s1, v19
	s_lshl_b32 s1, s0, 8
	v_subrev_u32_e32 v153, s1, v18
	v_add_u32_e32 v18, v101, v97
	s_lshl_b32 s1, s0, 6
	v_sub_u32_e32 v18, v18, v139
	v_subrev_u32_e32 v18, s1, v18
	v_mov_b32_e32 v20, v1
	v_mov_b32_e32 v21, v1
	s_add_i32 s44, s0, -2
	s_add_i32 s4, s1, s55
	v_add_u32_e32 v155, 0x8d, v18
	s_mul_i32 s0, s0, 0xac000
	s_mul_i32 s54, s54, 0xac000
	v_mov_b32_e32 v18, v1
	v_mov_b32_e32 v19, v1
	v_mov_b64_e32 v[24:25], v[20:21]
	v_mov_b64_e32 v[28:29], v[20:21]
	v_mov_b64_e32 v[32:33], v[20:21]
	v_mov_b64_e32 v[36:37], v[20:21]
	v_mov_b64_e32 v[40:41], v[20:21]
	v_mov_b64_e32 v[44:45], v[20:21]
	v_mov_b64_e32 v[48:49], v[20:21]
	s_add_i32 s94, s4, 0xffffff00
	v_mul_u32_u24_e32 v156, 0x2b00, v99
	s_add_i32 s95, s0, s54
	v_mul_lo_u32 v157, v144, s75
	v_mov_b32_e32 v159, 0
	v_mov_b32_e32 v160, 0xf149f2ca
	v_mov_b64_e32 v[22:23], v[18:19]
	v_mov_b64_e32 v[26:27], v[18:19]
	v_mov_b64_e32 v[30:31], v[18:19]
	v_mov_b64_e32 v[34:35], v[18:19]
	v_mov_b64_e32 v[38:39], v[18:19]
	v_mov_b64_e32 v[42:43], v[18:19]
	v_mov_b64_e32 v[46:47], v[18:19]
	v_mov_b32_e32 v162, 0xf149f2ca
	v_mov_b32_e32 v161, 0
	s_branch .LBB0_601
